# v87 + S5 table build deferred out of P0b: odd workgroups build theirs after the pre-P1 barrier (replaces the start delay), even ones after their last P1 unit
# speedup vs baseline: 1.0014x; 1.0014x over previous
_Z10hybrid_fwd4Args:
	s_mov_b32 s72, s2
	v_writelane_b32 v252, s0, 3
	v_writelane_b32 v252, s1, 4
	s_load_dwordx2 s[2:3], s[0:1], 0xd8
	s_add_u32 s6, s0, 0xd8
	s_addc_u32 s7, s1, 0
	v_and_b32_e32 v234, 0x3ff, v0
	s_mov_b32 s77, s72
	s_waitcnt lgkmcnt(0)
	v_writelane_b32 v253, s2, 0
	v_readfirstlane_b32 s73, v234
	s_nop 0
	v_writelane_b32 v253, s3, 1
	s_and_b32 s2, s2, 7
	s_cmp_lg_u32 s2, 0
	s_cbranch_scc1 .LBB0_2
	s_load_dwordx2 s[2:3], s[0:1], 0xd8
	s_waitcnt lgkmcnt(0)
	s_ashr_i32 s3, s72, 31
	s_lshr_b32 s3, s3, 29
	s_add_i32 s3, s72, s3
	s_and_b32 s4, s3, -8
	s_ashr_i32 s2, s2, 3
	s_sub_i32 s4, s72, s4
	s_mul_i32 s2, s2, s4
	s_ashr_i32 s3, s3, 3
	s_add_i32 s77, s2, s3

.LBB0_88:
	v_writelane_b32 v253, s27, 23
	v_writelane_b32 v253, s26, 24
	v_writelane_b32 v253, s36, 25
	s_add_u32 s0, s22, 0x40000
	s_addc_u32 s1, s23, 0
	v_writelane_b32 v253, s37, 26
	v_writelane_b32 v253, s38, 27
	v_writelane_b32 v253, s39, 28
	v_writelane_b32 v253, s40, 29
	v_writelane_b32 v253, s41, 30
	v_writelane_b32 v253, s42, 31
	v_writelane_b32 v253, s43, 32
	v_writelane_b32 v253, s44, 33
	v_writelane_b32 v253, s45, 34
	v_writelane_b32 v253, s46, 35
	v_writelane_b32 v253, s47, 36
	v_writelane_b32 v253, s48, 37
	v_writelane_b32 v253, s49, 38
	v_writelane_b32 v253, s50, 39
	v_writelane_b32 v253, s51, 40
	v_writelane_b32 v253, s76, 41
	v_writelane_b32 v253, s74, 42
	s_barrier
	s_nop 0
	v_writelane_b32 v253, s75, 43
	v_writelane_b32 v253, s0, 44
	s_nop 1
	v_writelane_b32 v253, s1, 45
	s_add_u32 s0, s22, 0x50000
	s_addc_u32 s1, s23, 0
	v_writelane_b32 v253, s0, 46
	s_nop 1
	v_writelane_b32 v253, s1, 47
	s_add_u32 s0, s22, 0x1600000
	v_writelane_b32 v253, s0, 48
	s_addc_u32 s0, s23, 0
	v_writelane_b32 v253, s0, 49
	s_add_u32 s0, s22, 0x1e00000
	v_writelane_b32 v253, s0, 50
	s_addc_u32 s0, s23, 0
	v_writelane_b32 v253, s0, 51
	s_add_u32 s0, s22, 0x2200000
	v_writelane_b32 v253, s0, 52
	s_addc_u32 s0, s23, 0
	v_writelane_b32 v253, s0, 53
	s_cmpk_gt_i32 s77, 0xff
	v_writelane_b32 v253, s77, 54
	s_cselect_b64 s[0:1], -1, 0
	v_writelane_b32 v253, s0, 55
	s_and_b64 vcc, exec, s[0:1]
	s_nop 0
	v_writelane_b32 v253, s1, 56
	v_writelane_b32 v253, s78, 57
	s_branch .LBB0_173
.Lmy_tab_entry:
	v_readlane_b32 s0, v253, 24
	s_lshl_b32 s49, s0, 8
	s_add_i32 s50, s49, 0
	s_add_i32 s1, s50, 0x2200
	v_writelane_b32 v253, s1, 58
	s_lshl_b32 s1, s0, 11
	v_writelane_b32 v253, s1, 59
	s_lshl_b32 s0, s0, 9
	v_writelane_b32 v253, s0, 60
	s_mov_b32 s82, 0x652b82fe
	s_mov_b32 s80, 0xfefa39ef
	s_mov_b32 s34, 0x3b39803f
	s_mov_b32 s26, 0x6a5dcb37
	s_mov_b32 s28, 0x6dc9c883
	s_mov_b32 s30, 0x54442d18
	s_mov_b32 s40, 0
	s_mov_b32 s42, 0
	v_readlane_b32 s72, v253, 54
	s_add_i32 s51, s50, 0x4200
	v_mov_b32_e32 v1, 0
	s_mov_b32 s83, 0x3ff71547
	s_mov_b32 s81, 0xbfe62e42
	s_mov_b32 s35, 0xbc7abc9e
	v_mov_b32_e32 v2, 0xfca7ab0c
	v_mov_b32_e32 v3, 0x3e928af3
	s_mov_b32 s27, 0x3e5ade15
	v_mov_b32_e32 v4, 0x623fde64
	v_mov_b32_e32 v5, 0x3ec71dee
	v_mov_b32_e32 v6, 0x7c89e6b0
	v_mov_b32_e32 v7, 0x3efa0199
	v_mov_b32_e32 v8, 0x14761f6e
	v_mov_b32_e32 v9, 0x3f2a01a0
	v_mov_b32_e32 v10, 0x1852b7b0
	v_mov_b32_e32 v11, 0x3f56c16c
	v_mov_b32_e32 v12, 0x11122322
	v_mov_b32_e32 v13, 0x3f811111
	v_mov_b32_e32 v14, 0x555502a1
	v_mov_b32_e32 v15, 0x3fa55555
	v_mov_b32_e32 v16, 0x55555511
	v_mov_b32_e32 v17, 0x3fc55555
	v_mov_b32_e32 v18, 11
	v_mov_b32_e32 v19, 0x3fe00000
	v_mov_b32_e32 v30, 0x7ff00000
	s_mov_b32 s29, 0x3fc45f30
	s_mov_b32 s31, 0x401921fb
	s_brev_b32 s38, 18
	s_mov_b32 s39, 0xfe5163ab
	s_mov_b32 s94, 0x3c439041
	s_mov_b32 s95, 0xdb629599
	s_mov_b32 s96, 0xf534ddc0
	s_mov_b32 s71, 0xfc2757d1
	s_mov_b32 s36, 0x4e441529
	s_mov_b32 s97, 0xa2f9836e
	s_mov_b32 s37, 0x3fc90fda
	s_mov_b32 s33, 0x3f22f983
	s_mov_b32 s46, 0xbfc90fda
	s_mov_b32 s41, 0x40900000
	s_mov_b32 s43, 0xc090cc00
	v_mov_b32_e32 v31, 0x3c0881c4
	v_mov_b32_e32 v32, 0xbab64f3b
	s_brev_b32 s47, 1
	s_movk_i32 s24, 0x1f8
	s_movk_i32 s25, 0x1ff
	s_mov_b64 s[44:45], 0x800
	s_movk_i32 s68, 0x7fff
	s_mov_b32 s69, 0xffff0000
	s_mov_b32 s70, 0x7ffff0
	v_not_b32_e32 v33, 63
	v_not_b32_e32 v34, 31
	v_mov_b32_e32 v35, 0x7fc00000
	s_mov_b32 s48, s72
	s_branch .LBB0_91

.Lmy_tab_ret:
	v_readlane_b32 s98, v252, 59
	v_readlane_b32 s99, v252, 60
	v_readlane_b32 s100, v252, 61
	s_nop 1
	v_writelane_b32 v253, s98, 58
	v_writelane_b32 v253, s99, 59
	v_writelane_b32 v253, s100, 60
	v_readlane_b32 s0, v252, 5
	v_readlane_b32 s1, v252, 6
	v_readlane_b32 s4, v252, 7
	v_readlane_b32 s5, v252, 8
	v_readlane_b32 s14, v252, 9
	v_readlane_b32 s16, v252, 10
	v_readlane_b32 s19, v252, 11
	v_readlane_b32 s26, v252, 12
	v_readlane_b32 s27, v252, 13
	v_readlane_b32 s28, v252, 14
	v_readlane_b32 s29, v252, 15
	v_readlane_b32 s30, v252, 16
	v_readlane_b32 s31, v252, 17
	v_readlane_b32 s33, v252, 18
	v_readlane_b32 s34, v252, 19
	v_readlane_b32 s35, v252, 20
	v_readlane_b32 s36, v252, 21
	v_readlane_b32 s38, v252, 22
	v_readlane_b32 s44, v252, 23
	v_readlane_b32 s45, v252, 24
	v_readlane_b32 s46, v252, 25
	v_readlane_b32 s47, v252, 26
	v_readlane_b32 s48, v252, 27
	v_readlane_b32 s49, v252, 28
	v_readlane_b32 s52, v252, 29
	v_readlane_b32 s53, v252, 30
	v_readlane_b32 s54, v252, 31
	v_readlane_b32 s55, v252, 32
	v_readlane_b32 s56, v252, 33
	v_readlane_b32 s57, v252, 34
	v_readlane_b32 s58, v252, 35
	v_readlane_b32 s59, v252, 36
	v_readlane_b32 s60, v252, 37
	v_readlane_b32 s61, v252, 38
	v_readlane_b32 s72, v252, 39
	v_readlane_b32 s73, v252, 40
	v_readlane_b32 s74, v252, 41
	v_readlane_b32 s75, v252, 42
	v_readlane_b32 s76, v252, 43
	v_readlane_b32 s82, v252, 44
	v_readlane_b32 s83, v252, 45
	v_readlane_b32 s84, v252, 46
	v_readlane_b32 s85, v252, 47
	v_readlane_b32 s86, v252, 48
	v_readlane_b32 s87, v252, 49
	v_readlane_b32 s88, v252, 50
	v_readlane_b32 s89, v252, 51
	v_readlane_b32 s90, v252, 52
	v_readlane_b32 s91, v252, 53
	v_readlane_b32 s92, v252, 54
	v_readlane_b32 s93, v252, 55
	v_readlane_b32 s94, v252, 56
	v_readlane_b32 s96, v252, 57
	v_readlane_b32 s97, v252, 58
	v_mov_b32_e32 v3, v254
	v_mov_b32_e32 v8, v255
	s_mov_b64 exec, -1
	s_nop 4
	s_cmp_eq_u32 s101, 0
	s_cbranch_scc1 .Lmy_tab_ret1
	s_branch .Lmy_tab_ret2

.LBB0_255:
	s_or_b64 exec, exec, s[4:5]
	s_cmpk_lt_i32 s97, 0xc00
	v_mov_b32_e32 v8, v234
	s_cselect_b64 s[4:5], -1, 0
	s_cmpk_gt_i32 s97, 0xbff
	s_waitcnt lgkmcnt(0)
	s_barrier
	s_bitcmp1_b32 s97, 0
	s_cbranch_scc0 .Lmy_p1_go
	v_writelane_b32 v252, s0, 5
	v_writelane_b32 v252, s1, 6
	v_writelane_b32 v252, s4, 7
	v_writelane_b32 v252, s5, 8
	v_writelane_b32 v252, s14, 9
	v_writelane_b32 v252, s16, 10
	v_writelane_b32 v252, s19, 11
	v_writelane_b32 v252, s26, 12
	v_writelane_b32 v252, s27, 13
	v_writelane_b32 v252, s28, 14
	v_writelane_b32 v252, s29, 15
	v_writelane_b32 v252, s30, 16
	v_writelane_b32 v252, s31, 17
	v_writelane_b32 v252, s33, 18
	v_writelane_b32 v252, s34, 19
	v_writelane_b32 v252, s35, 20
	v_writelane_b32 v252, s36, 21
	v_writelane_b32 v252, s38, 22
	v_writelane_b32 v252, s44, 23
	v_writelane_b32 v252, s45, 24
	v_writelane_b32 v252, s46, 25
	v_writelane_b32 v252, s47, 26
	v_writelane_b32 v252, s48, 27
	v_writelane_b32 v252, s49, 28
	v_writelane_b32 v252, s52, 29
	v_writelane_b32 v252, s53, 30
	v_writelane_b32 v252, s54, 31
	v_writelane_b32 v252, s55, 32
	v_writelane_b32 v252, s56, 33
	v_writelane_b32 v252, s57, 34
	v_writelane_b32 v252, s58, 35
	v_writelane_b32 v252, s59, 36
	v_writelane_b32 v252, s60, 37
	v_writelane_b32 v252, s61, 38
	v_writelane_b32 v252, s72, 39
	v_writelane_b32 v252, s73, 40
	v_writelane_b32 v252, s74, 41
	v_writelane_b32 v252, s75, 42
	v_writelane_b32 v252, s76, 43
	v_writelane_b32 v252, s82, 44
	v_writelane_b32 v252, s83, 45
	v_writelane_b32 v252, s84, 46
	v_writelane_b32 v252, s85, 47
	v_writelane_b32 v252, s86, 48
	v_writelane_b32 v252, s87, 49
	v_writelane_b32 v252, s88, 50
	v_writelane_b32 v252, s89, 51
	v_writelane_b32 v252, s90, 52
	v_writelane_b32 v252, s91, 53
	v_writelane_b32 v252, s92, 54
	v_writelane_b32 v252, s93, 55
	v_writelane_b32 v252, s94, 56
	v_writelane_b32 v252, s96, 57
	v_writelane_b32 v252, s97, 58
	v_readlane_b32 s98, v253, 58
	v_readlane_b32 s99, v253, 59
	v_readlane_b32 s100, v253, 60
	s_nop 1
	v_writelane_b32 v252, s98, 59
	v_writelane_b32 v252, s99, 60
	v_writelane_b32 v252, s100, 61
	v_mov_b32_e32 v254, v3
	v_mov_b32_e32 v255, v8
	s_mov_b32 s101, 0
	v_readlane_b32 s98, v252, 3
	v_readlane_b32 s99, v252, 4
	s_nop 4
	s_load_dwordx8 s[52:59], s[98:99], 0x80
	s_load_dwordx2 s[60:61], s[98:99], 0xa0
	v_readfirstlane_b32 s78, v234
	s_mov_b64 exec, -1
	s_nop 1
	s_and_b32 s78, s78, 0xffffffc0
	s_waitcnt lgkmcnt(0)
	s_branch .Lmy_tab_entry
.Lmy_tab_ret1:
.Lmy_p1_go:
	s_cmpk_gt_i32 s97, 0xbff
	s_cbranch_scc1 .LBB0_257
	s_ashr_i32 s2, s97, 31
	s_lshr_b32 s2, s2, 29
	s_add_i32 s2, s97, s2
	s_ashr_i32 s3, s2, 3
	s_and_b32 s2, s2, -8
	s_sub_i32 s2, s97, s2
	s_cmp_lt_i32 s2, 0
	s_movk_i32 s6, 0x181
	s_cselect_b32 s6, s6, 0x180
	s_mul_i32 s2, s2, s6
	s_add_i32 s2, s2, s3
	s_mul_hi_i32 s3, s2, 0x2aaaaaab
	s_lshr_b32 s6, s3, 31
	s_ashr_i32 s3, s3, 5
	s_add_i32 s3, s3, s6
	s_lshl_b32 s6, s3, 3
	s_mulk_i32 s3, 0xc0
	s_sub_i32 s2, s2, s3
	s_sext_i32_i16 s3, s2
	s_bfe_u32 s3, s3, 0x3001c
	s_add_i32 s3, s2, s3
	s_sext_i32_i16 s7, s3
	s_and_b32 s3, s3, 0xfff8
	s_sub_i32 s2, s2, s3
	s_sext_i32_i16 s2, s2
	s_add_i32 s52, s6, s2
	s_ashr_i32 s46, s7, 3

.LBB0_565:
	s_bitcmp1_b32 s97, 0
	s_cbranch_scc1 .Lmy_b3_go
	v_writelane_b32 v252, s0, 5
	v_writelane_b32 v252, s1, 6
	v_writelane_b32 v252, s4, 7
	v_writelane_b32 v252, s5, 8
	v_writelane_b32 v252, s14, 9
	v_writelane_b32 v252, s16, 10
	v_writelane_b32 v252, s19, 11
	v_writelane_b32 v252, s26, 12
	v_writelane_b32 v252, s27, 13
	v_writelane_b32 v252, s28, 14
	v_writelane_b32 v252, s29, 15
	v_writelane_b32 v252, s30, 16
	v_writelane_b32 v252, s31, 17
	v_writelane_b32 v252, s33, 18
	v_writelane_b32 v252, s34, 19
	v_writelane_b32 v252, s35, 20
	v_writelane_b32 v252, s36, 21
	v_writelane_b32 v252, s38, 22
	v_writelane_b32 v252, s44, 23
	v_writelane_b32 v252, s45, 24
	v_writelane_b32 v252, s46, 25
	v_writelane_b32 v252, s47, 26
	v_writelane_b32 v252, s48, 27
	v_writelane_b32 v252, s49, 28
	v_writelane_b32 v252, s52, 29
	v_writelane_b32 v252, s53, 30
	v_writelane_b32 v252, s54, 31
	v_writelane_b32 v252, s55, 32
	v_writelane_b32 v252, s56, 33
	v_writelane_b32 v252, s57, 34
	v_writelane_b32 v252, s58, 35
	v_writelane_b32 v252, s59, 36
	v_writelane_b32 v252, s60, 37
	v_writelane_b32 v252, s61, 38
	v_writelane_b32 v252, s72, 39
	v_writelane_b32 v252, s73, 40
	v_writelane_b32 v252, s74, 41
	v_writelane_b32 v252, s75, 42
	v_writelane_b32 v252, s76, 43
	v_writelane_b32 v252, s82, 44
	v_writelane_b32 v252, s83, 45
	v_writelane_b32 v252, s84, 46
	v_writelane_b32 v252, s85, 47
	v_writelane_b32 v252, s86, 48
	v_writelane_b32 v252, s87, 49
	v_writelane_b32 v252, s88, 50
	v_writelane_b32 v252, s89, 51
	v_writelane_b32 v252, s90, 52
	v_writelane_b32 v252, s91, 53
	v_writelane_b32 v252, s92, 54
	v_writelane_b32 v252, s93, 55
	v_writelane_b32 v252, s94, 56
	v_writelane_b32 v252, s96, 57
	v_writelane_b32 v252, s97, 58
	v_readlane_b32 s98, v253, 58
	v_readlane_b32 s99, v253, 59
	v_readlane_b32 s100, v253, 60
	s_nop 1
	v_writelane_b32 v252, s98, 59
	v_writelane_b32 v252, s99, 60
	v_writelane_b32 v252, s100, 61
	v_mov_b32_e32 v254, v3
	v_mov_b32_e32 v255, v8
	s_mov_b32 s101, 1
	v_readlane_b32 s98, v252, 3
	v_readlane_b32 s99, v252, 4
	s_nop 4
	s_load_dwordx8 s[52:59], s[98:99], 0x80
	s_load_dwordx2 s[60:61], s[98:99], 0xa0
	v_readfirstlane_b32 s78, v234
	s_mov_b64 exec, -1
	s_nop 1
	s_and_b32 s78, s78, 0xffffffc0
	s_waitcnt lgkmcnt(0)
	s_branch .Lmy_tab_entry
.Lmy_tab_ret2:
.Lmy_b3_go:
	s_waitcnt vmcnt(0)
	s_waitcnt vmcnt(0)
	s_barrier
	s_mov_b64 s[4:5], exec
	v_readlane_b32 s2, v253, 3
	v_readlane_b32 s3, v253, 4
	s_and_b64 s[2:3], s[4:5], s[2:3]
	s_mov_b64 s[82:83], s[72:73]
	s_mov_b64 exec, s[2:3]
	s_cbranch_execz .LBB0_617
	s_add_i32 s2, 0, 0x23ff0
	v_mov_b32_e32 v0, s2
	s_waitcnt vmcnt(0) expcnt(0) lgkmcnt(0)
	ds_read_b32 v2, v0
	s_add_i32 s2, 0, 0x23ff4
	v_mov_b32_e32 v0, s2
	ds_read_b32 v0, v0
	s_waitcnt lgkmcnt(1)
	v_cmp_ne_u32_e32 vcc, 0, v2
	s_cbranch_vccnz .LBB0_581
	s_add_u32 s6, s22, 0x100200
	s_addc_u32 s7, s23, 0
	s_add_u32 s8, s22, 0x100400
	s_addc_u32 s9, s23, 0
	s_add_u32 s10, s22, 0x100500
	s_addc_u32 s11, s23, 0
	s_add_u32 s14, s22, 0x100600
	s_addc_u32 s15, s23, 0
	s_add_u32 s16, s22, 0x100700
	s_addc_u32 s17, s23, 0
	s_add_u32 s42, s22, 0x100800
	s_addc_u32 s43, s23, 0
	s_add_u32 s44, s22, 0x100900
	s_addc_u32 s45, s23, 0
	s_add_u32 s46, s22, 0x100a00
	s_addc_u32 s47, s23, 0
	s_add_u32 s48, s22, 0x100b00
	s_addc_u32 s49, s23, 0
	s_add_u32 s50, s22, 0x100c00
	s_addc_u32 s51, s23, 0
	s_add_u32 s52, s22, 0x100d00
	s_addc_u32 s53, s23, 0
	s_add_u32 s54, s22, 0x100e00
	s_addc_u32 s55, s23, 0
	s_add_u32 s56, s22, 0x100f00
	s_addc_u32 s57, s23, 0
	s_add_u32 s58, s22, 0x101000
	s_addc_u32 s59, s23, 0
	s_add_u32 s60, s22, 0x101100
	s_addc_u32 s61, s23, 0
	s_add_u32 s62, s22, 0x101200
	v_readlane_b32 s2, v253, 2
	s_addc_u32 s63, s23, 0
	s_mul_i32 s2, s83, s2
	s_add_u32 s66, s22, 0x101300
	s_mul_i32 s2, s2, s82
	s_addc_u32 s67, s23, 0
	s_mov_b32 s3, 1
	v_mov_b32_e32 v16, 0
	s_branch .LBB0_569
